# v17 + first K-loop iteration peeled in P1/P4/P5 with C=0 first-touch MFMAs (no 128-v_mov accumulator zeroing per tile)
# speedup vs baseline: 1.0091x; 1.0091x over previous
; #define PG8_STAGE(bufoff, gbase, voff) do { _Pragma("unroll") for (int _i = 0; _i < 2; ++_i) \
;         __builtin_amdgcn_global_load_lds((const unsigned*)((const char*)(gbase) + (voff)[_i]), (PG8_LAS unsigned*)(lds + (bufoff) + ldsw + _i * 8192), 16, 0, 0); } while (0)
; #define PG8_LDA(dst, b, h) do { _Pragma("unroll") for (int m = 0; m < 4; ++m) _Pragma("unroll") for (int k = 0; k < 2; ++k) dst[m][k] = *(const PG8_LAS bf16x8*)(lds + PG8_SA(b, h) + aoff + m * 2048 + k * 1024); } while (0)
; #define PG8_LDB(dst, b, h) do { _Pragma("unroll") for (int n = 0; n < 2; ++n) _Pragma("unroll") for (int k = 0; k < 2; ++k) dst[n][k] = *(const PG8_LAS bf16x8*)(lds + PG8_SB(b, h) + boff + n * 2048 + k * 1024); } while (0)
; #define PG8_WAIT_V(n) asm volatile("s_waitcnt vmcnt(" #n ")" ::: "memory")
; #define PG8_WAIT_L(n) asm volatile("s_waitcnt lgkmcnt(" #n ")" ::: "memory")
; #define PG8_BAR __builtin_amdgcn_s_barrier()
; template <class Epi, class Sched, bool ALIGN_EPI = false, bool SP2 = false, bool ABLK = false>
; __device__ __forceinline__ void gemm_phase(PG8_LAS unsigned char* lds, const Gemm g, const Sched& S, const Epi& E) {
;     ...
;         const char* nA = has_next ? (const char*)g.A + (size_t)nxt.pm * tstepA : cA; const char* nB = has_next ? (const char*)g.Bt + (size_t)nxt.pn * tstep : cB;
;         for (int t = 0; t < nt; t += 2) {
;             if constexpr (Epi::MID) { if (t == nt / 2) E.mid(acc, cur, wr, wc, fr, fq); }
;             const bool last = (t == nt - 2);
;             const char* a1 = cA + (size_t)(t + 1) * kstepA;
;             const char* a2 = last ? nA : cA + (size_t)(t + 2) * kstepA; const char* b2 = last ? nB : cB + (size_t)(t + 2) * kstep;
;             const char* a3 = a2 + kstepA; const char* b3 = b2 + kstep;
;             if (last && has_next) S.a_ready(nxt);
;             if constexpr (SP2) {
;             PG8_LDB(B0, 0, 0); PG8_LDB(B1, 0, 1); PG8_SCHED; PG8_LDA(At, 0, 0); PG8_STAGE(PG8_SA(1, 1), a1 + hstepA, voffA);
;             PG8_WAIT_V(8); PG8_WAIT_L(0); PG8_BAR; PG8_MMA(0, 0, At, B0); PG8_MMA(0, 1, At, B1); PG8_BAR; PG8_SCHED;
;             PG8_LDA(At, 0, 1); PG8_STAGE(PG8_SB(0, 0), b2, voffB); PG8_STAGE(PG8_SB(0, 1), b2 + hstep, voffB); PG8_STAGE(PG8_SA(0, 0), a2, voffA);
;             PG8_WAIT_V(8); PG8_WAIT_L(0); PG8_BAR; PG8_MMA(1, 0, At, B0); PG8_MMA(1, 1, At, B1); PG8_BAR; PG8_SCHED;
.LBB0_214:
	s_ashr_i32 s5, s4, 31
	s_lshl_b64 s[6:7], s[4:5], 19
	s_add_u32 s8, s62, s6
	s_addc_u32 s9, s63, s7
	s_and_b64 s[6:7], s[36:37], exec
	s_cselect_b32 s5, s9, s99
	s_cselect_b32 s21, s8, s98
	s_ashr_i32 s95, s94, 31
	s_lshl_b64 s[6:7], s[94:95], 19
	s_add_u32 s6, s74, s6
	s_addc_u32 s7, s75, s7
	s_and_b64 s[22:23], s[36:37], exec
	s_cselect_b32 s95, s7, s1
	s_cselect_b32 s22, s6, s0
	s_add_u32 vcc_lo, s98, 0x40080
	s_addc_u32 vcc_hi, s99, 0
	s_add_u32 s23, s0, 0x100
	s_addc_u32 s24, s1, 0
	s_mov_b32 s25, -2
	ds_read_b128 v[166:169], v163
	ds_read_b128 v[170:173], v163 offset:1024
	ds_read_b128 v[180:183], v163 offset:2048
	ds_read_b128 v[184:187], v163 offset:3072
	ds_read_b128 v[188:191], v164
	ds_read_b128 v[192:195], v164 offset:1024
	ds_read_b128 v[196:199], v164 offset:2048
	ds_read_b128 v[200:203], v164 offset:3072
	s_add_u32 s0, vcc_lo, 0xfffc0080
	s_addc_u32 s1, vcc_hi, -1
	s_cmp_eq_u32 s25, 12
	s_cselect_b32 s99, s5, s1
	s_cselect_b32 s98, s21, s0
	s_cselect_b32 s1, s95, s24
	s_cselect_b32 s0, s22, s23
	v_lshl_add_u64 v[176:177], vcc, 0, v[142:143]
	s_add_i32 m0, s97, 0xc000
	ds_read_b128 v[204:207], v165
	ds_read_b128 v[208:211], v165 offset:1024
	ds_read_b128 v[212:215], v165 offset:2048
	ds_read_b128 v[216:219], v165 offset:3072
	ds_read_b128 v[220:223], v165 offset:4096
	ds_read_b128 v[224:227], v165 offset:5120
	ds_read_b128 v[228:231], v165 offset:6144
	ds_read_b128 v[232:235], v165 offset:7168
	global_load_lds_dwordx4 v[176:177], off
	v_lshl_add_u64 v[176:177], vcc, 0, v[144:145]
	s_add_i32 m0, s97, 0xe000
	s_nop 0
	global_load_lds_dwordx4 v[176:177], off
	s_waitcnt vmcnt(8)
	s_waitcnt lgkmcnt(0)
	s_barrier
	s_setprio 1
	s_waitcnt lgkmcnt(0)
	v_mfma_f32_16x16x32_bf16 v[124:127], v[166:169], v[204:207], 0
	v_mfma_f32_16x16x32_bf16 v[120:123], v[180:183], v[204:207], 0
	v_mfma_f32_16x16x32_bf16 v[116:119], v[166:169], v[212:215], 0
	v_mfma_f32_16x16x32_bf16 v[108:111], v[180:183], v[212:215], 0
	v_mfma_f32_16x16x32_bf16 v[100:103], v[166:169], v[220:223], 0
	v_mfma_f32_16x16x32_bf16 v[92:95], v[180:183], v[220:223], 0
	v_mfma_f32_16x16x32_bf16 v[84:87], v[166:169], v[228:231], 0
	v_mfma_f32_16x16x32_bf16 v[76:79], v[180:183], v[228:231], 0
	v_mfma_f32_16x16x32_bf16 v[124:127], v[170:173], v[208:211], v[124:127]
	v_mfma_f32_16x16x32_bf16 v[120:123], v[184:187], v[208:211], v[120:123]
	v_mfma_f32_16x16x32_bf16 v[116:119], v[170:173], v[216:219], v[116:119]
	v_mfma_f32_16x16x32_bf16 v[108:111], v[184:187], v[216:219], v[108:111]
	v_mfma_f32_16x16x32_bf16 v[100:103], v[170:173], v[224:227], v[100:103]
	v_mfma_f32_16x16x32_bf16 v[92:95], v[184:187], v[224:227], v[92:95]
	v_mfma_f32_16x16x32_bf16 v[84:87], v[170:173], v[232:235], v[84:87]
	v_mfma_f32_16x16x32_bf16 v[76:79], v[184:187], v[232:235], v[76:79]
	s_setprio 0
	s_setprio 1
	v_mfma_f32_16x16x32_bf16 v[112:115], v[188:191], v[204:207], 0
	v_mfma_f32_16x16x32_bf16 v[104:107], v[196:199], v[204:207], 0
	v_mfma_f32_16x16x32_bf16 v[96:99], v[188:191], v[212:215], 0
	v_mfma_f32_16x16x32_bf16 v[88:91], v[196:199], v[212:215], 0
	v_mfma_f32_16x16x32_bf16 v[80:83], v[188:191], v[220:223], 0
	v_mfma_f32_16x16x32_bf16 v[72:75], v[196:199], v[220:223], 0
	v_mfma_f32_16x16x32_bf16 v[68:71], v[188:191], v[228:231], 0
	v_mfma_f32_16x16x32_bf16 v[64:67], v[196:199], v[228:231], 0
	v_mfma_f32_16x16x32_bf16 v[112:115], v[192:195], v[208:211], v[112:115]
	v_mfma_f32_16x16x32_bf16 v[104:107], v[200:203], v[208:211], v[104:107]
	v_mfma_f32_16x16x32_bf16 v[96:99], v[192:195], v[216:219], v[96:99]
	v_mfma_f32_16x16x32_bf16 v[88:91], v[200:203], v[216:219], v[88:91]
	v_mfma_f32_16x16x32_bf16 v[80:83], v[192:195], v[224:227], v[80:83]
	v_mfma_f32_16x16x32_bf16 v[72:75], v[200:203], v[224:227], v[72:75]
	v_mfma_f32_16x16x32_bf16 v[68:71], v[192:195], v[232:235], v[68:71]
	v_mfma_f32_16x16x32_bf16 v[64:67], v[200:203], v[232:235], v[64:67]
	s_setprio 0
	s_barrier
	s_add_i32 s26, s17, s46
	v_lshl_add_u64 v[176:177], s[0:1], 0, v[136:137]
	s_mov_b32 m0, s26
	ds_read_b128 v[204:207], v165 offset:16384
	ds_read_b128 v[208:211], v165 offset:17408
	ds_read_b128 v[212:215], v165 offset:18432
	ds_read_b128 v[216:219], v165 offset:19456
	ds_read_b128 v[220:223], v165 offset:20480
	ds_read_b128 v[224:227], v165 offset:21504
	ds_read_b128 v[228:231], v165 offset:22528
	ds_read_b128 v[232:235], v165 offset:23552
	global_load_lds_dwordx4 v[176:177], off
	s_add_i32 m0, s26, 0x2000
	s_add_u32 s26, s0, 0x40000
	v_lshl_add_u64 v[236:237], s[0:1], 0, v[132:133]
	s_addc_u32 s27, s1, 0
	s_add_i32 s28, s18, s46
	global_load_lds_dwordx4 v[236:237], off
	v_lshl_add_u64 v[238:239], s[26:27], 0, v[136:137]
	s_mov_b32 m0, s28
	v_lshl_add_u64 v[240:241], s[98:99], 0, v[134:135]
	global_load_lds_dwordx4 v[238:239], off
	v_lshl_add_u64 v[238:239], s[26:27], 0, v[132:133]
	s_add_i32 m0, s28, 0x2000
	s_nop 0
	global_load_lds_dwordx4 v[238:239], off
	v_lshl_add_u64 v[238:239], s[98:99], 0, v[138:139]
	s_mov_b32 m0, s97
	s_nop 0
	global_load_lds_dwordx4 v[238:239], off
	s_mov_b32 m0, s10
	s_nop 0
	global_load_lds_dwordx4 v[240:241], off
	s_waitcnt vmcnt(8)
	s_waitcnt lgkmcnt(0)
	s_barrier
; #define PG8_STAGE(bufoff, gbase, voff) do { _Pragma("unroll") for (int _i = 0; _i < 2; ++_i) \
;         __builtin_amdgcn_global_load_lds((const unsigned*)((const char*)(gbase) + (voff)[_i]), (PG8_LAS unsigned*)(lds + (bufoff) + ldsw + _i * 8192), 16, 0, 0); } while (0)
; #define PG8_LDA(dst, b, h) do { _Pragma("unroll") for (int m = 0; m < 4; ++m) _Pragma("unroll") for (int k = 0; k < 2; ++k) dst[m][k] = *(const PG8_LAS bf16x8*)(lds + PG8_SA(b, h) + aoff + m * 2048 + k * 1024); } while (0)
; #define PG8_LDB(dst, b, h) do { _Pragma("unroll") for (int n = 0; n < 2; ++n) _Pragma("unroll") for (int k = 0; k < 2; ++k) dst[n][k] = *(const PG8_LAS bf16x8*)(lds + PG8_SB(b, h) + boff + n * 2048 + k * 1024); } while (0)
; #define PG8_MMA(ai, bj, At, Bt) do { __builtin_amdgcn_s_setprio(1); _Pragma("unroll") for (int m = 0; m < 4; ++m) _Pragma("unroll") for (int n = 0; n < 2; ++n) _Pragma("unroll") for (int k = 0; k < 2; ++k) \
;         acc[ai][bj][m][n] = __builtin_amdgcn_mfma_f32_16x16x32_bf16(Bt[n][k], At[m][k], acc[ai][bj][m][n], 0, 0, 0); __builtin_amdgcn_s_setprio(0); } while (0)
; #define PG8_WAIT_V(n) asm volatile("s_waitcnt vmcnt(" #n ")" ::: "memory")
; #define PG8_WAIT_L(n) asm volatile("s_waitcnt lgkmcnt(" #n ")" ::: "memory")
; #define PG8_BAR __builtin_amdgcn_s_barrier()
; #define PG8_SCHED __builtin_amdgcn_sched_barrier(0)
; template <class Epi, class Sched, bool ALIGN_EPI = false, bool SP2 = false, bool ABLK = false>
; __device__ __forceinline__ void gemm_phase(PG8_LAS unsigned char* lds, const Gemm g, const Sched& S, const Epi& E) {
;     ...
;             PG8_WAIT_V(8); PG8_WAIT_L(0); PG8_BAR; PG8_MMA(1, 0, At, B0); PG8_MMA(1, 1, At, B1); PG8_BAR; PG8_SCHED;
;             PG8_LDB(B0, 1, 0); PG8_LDB(B1, 1, 1); PG8_SCHED; PG8_LDA(At, 1, 0); PG8_STAGE(PG8_SA(0, 1), a2 + hstepA, voffA);
;             PG8_WAIT_V(8); PG8_WAIT_L(0); PG8_BAR; PG8_MMA(0, 0, At, B0); PG8_MMA(0, 1, At, B1); PG8_BAR; PG8_SCHED;
	s_setprio 1
	s_waitcnt lgkmcnt(0)
	v_mfma_f32_16x16x32_bf16 v[60:63], v[166:169], v[204:207], 0
	v_mfma_f32_16x16x32_bf16 v[56:59], v[180:183], v[204:207], 0
	v_mfma_f32_16x16x32_bf16 v[52:55], v[166:169], v[212:215], 0
	v_mfma_f32_16x16x32_bf16 v[44:47], v[180:183], v[212:215], 0
	v_mfma_f32_16x16x32_bf16 v[36:39], v[166:169], v[220:223], 0
	v_mfma_f32_16x16x32_bf16 v[28:31], v[180:183], v[220:223], 0
	v_mfma_f32_16x16x32_bf16 v[20:23], v[166:169], v[228:231], 0
	v_mfma_f32_16x16x32_bf16 v[12:15], v[180:183], v[228:231], 0
	v_mfma_f32_16x16x32_bf16 v[60:63], v[170:173], v[208:211], v[60:63]
	v_mfma_f32_16x16x32_bf16 v[56:59], v[184:187], v[208:211], v[56:59]
	v_mfma_f32_16x16x32_bf16 v[52:55], v[170:173], v[216:219], v[52:55]
	v_mfma_f32_16x16x32_bf16 v[44:47], v[184:187], v[216:219], v[44:47]
	v_mfma_f32_16x16x32_bf16 v[36:39], v[170:173], v[224:227], v[36:39]
	v_mfma_f32_16x16x32_bf16 v[28:31], v[184:187], v[224:227], v[28:31]
	v_mfma_f32_16x16x32_bf16 v[20:23], v[170:173], v[232:235], v[20:23]
	v_mfma_f32_16x16x32_bf16 v[12:15], v[184:187], v[232:235], v[12:15]
	s_setprio 0
	s_setprio 1
	v_mfma_f32_16x16x32_bf16 v[48:51], v[188:191], v[204:207], 0
	v_mfma_f32_16x16x32_bf16 v[40:43], v[196:199], v[204:207], 0
	v_mfma_f32_16x16x32_bf16 v[32:35], v[188:191], v[212:215], 0
	v_mfma_f32_16x16x32_bf16 v[24:27], v[196:199], v[212:215], 0
	v_mfma_f32_16x16x32_bf16 v[16:19], v[188:191], v[220:223], 0
	v_mfma_f32_16x16x32_bf16 v[8:11], v[196:199], v[220:223], 0
	v_mfma_f32_16x16x32_bf16 v[4:7], v[188:191], v[228:231], 0
	v_mfma_f32_16x16x32_bf16 v[0:3], v[196:199], v[228:231], 0
	v_mfma_f32_16x16x32_bf16 v[48:51], v[192:195], v[208:211], v[48:51]
	v_mfma_f32_16x16x32_bf16 v[40:43], v[200:203], v[208:211], v[40:43]
	v_mfma_f32_16x16x32_bf16 v[32:35], v[192:195], v[216:219], v[32:35]
	v_mfma_f32_16x16x32_bf16 v[24:27], v[200:203], v[216:219], v[24:27]
	v_mfma_f32_16x16x32_bf16 v[16:19], v[192:195], v[224:227], v[16:19]
	v_mfma_f32_16x16x32_bf16 v[8:11], v[200:203], v[224:227], v[8:11]
	v_mfma_f32_16x16x32_bf16 v[4:7], v[192:195], v[232:235], v[4:7]
	v_mfma_f32_16x16x32_bf16 v[0:3], v[200:203], v[232:235], v[0:3]
	s_setprio 0
	s_barrier
	s_add_i32 s28, 0, 0x18000
	v_add_u32_e32 v140, s28, v161
	s_add_i32 s29, 0, 0x1c000
	ds_read_b128 v[166:169], v140
	ds_read_b128 v[170:173], v140 offset:1024
	ds_read_b128 v[180:183], v140 offset:2048
	ds_read_b128 v[184:187], v140 offset:3072
	v_add_u32_e32 v140, s29, v161
	ds_read_b128 v[188:191], v140
	ds_read_b128 v[192:195], v140 offset:1024
	ds_read_b128 v[196:199], v140 offset:2048
	ds_read_b128 v[200:203], v140 offset:3072
	s_add_u32 s26, s98, 0x40000
	s_addc_u32 s27, s99, 0
	s_mov_b32 m0, s11
	v_lshl_add_u64 v[242:243], s[26:27], 0, v[138:139]
	ds_read_b128 v[204:207], v165 offset:32768
	ds_read_b128 v[208:211], v165 offset:33792
	ds_read_b128 v[212:215], v165 offset:34816
	ds_read_b128 v[216:219], v165 offset:35840
	ds_read_b128 v[220:223], v165 offset:36864
	ds_read_b128 v[224:227], v165 offset:37888
	ds_read_b128 v[228:231], v165 offset:38912
	ds_read_b128 v[232:235], v165 offset:39936
	global_load_lds_dwordx4 v[242:243], off
	v_lshl_add_u64 v[242:243], s[26:27], 0, v[134:135]
	s_mov_b32 m0, s12
	s_nop 0
	global_load_lds_dwordx4 v[242:243], off
	s_waitcnt vmcnt(8)
	s_waitcnt lgkmcnt(0)
	s_barrier
	s_setprio 1
	s_waitcnt lgkmcnt(0)
	v_mfma_f32_16x16x32_bf16 v[124:127], v[166:169], v[204:207], v[124:127]
	v_mfma_f32_16x16x32_bf16 v[120:123], v[180:183], v[204:207], v[120:123]
	v_mfma_f32_16x16x32_bf16 v[116:119], v[166:169], v[212:215], v[116:119]
	v_mfma_f32_16x16x32_bf16 v[108:111], v[180:183], v[212:215], v[108:111]
	v_mfma_f32_16x16x32_bf16 v[100:103], v[166:169], v[220:223], v[100:103]
	v_mfma_f32_16x16x32_bf16 v[92:95], v[180:183], v[220:223], v[92:95]
	v_mfma_f32_16x16x32_bf16 v[84:87], v[166:169], v[228:231], v[84:87]
	v_mfma_f32_16x16x32_bf16 v[76:79], v[180:183], v[228:231], v[76:79]
	v_mfma_f32_16x16x32_bf16 v[124:127], v[170:173], v[208:211], v[124:127]
	v_mfma_f32_16x16x32_bf16 v[120:123], v[184:187], v[208:211], v[120:123]
	v_mfma_f32_16x16x32_bf16 v[116:119], v[170:173], v[216:219], v[116:119]
	v_mfma_f32_16x16x32_bf16 v[108:111], v[184:187], v[216:219], v[108:111]
	v_mfma_f32_16x16x32_bf16 v[100:103], v[170:173], v[224:227], v[100:103]
	v_mfma_f32_16x16x32_bf16 v[92:95], v[184:187], v[224:227], v[92:95]
	v_mfma_f32_16x16x32_bf16 v[84:87], v[170:173], v[232:235], v[84:87]
	v_mfma_f32_16x16x32_bf16 v[76:79], v[184:187], v[232:235], v[76:79]
	s_setprio 0
	s_setprio 1
	v_mfma_f32_16x16x32_bf16 v[112:115], v[188:191], v[204:207], v[112:115]
	v_mfma_f32_16x16x32_bf16 v[104:107], v[196:199], v[204:207], v[104:107]
	v_mfma_f32_16x16x32_bf16 v[96:99], v[188:191], v[212:215], v[96:99]
	v_mfma_f32_16x16x32_bf16 v[88:91], v[196:199], v[212:215], v[88:91]
	v_mfma_f32_16x16x32_bf16 v[80:83], v[188:191], v[220:223], v[80:83]
	v_mfma_f32_16x16x32_bf16 v[72:75], v[196:199], v[220:223], v[72:75]
	v_mfma_f32_16x16x32_bf16 v[68:71], v[188:191], v[228:231], v[68:71]
	v_mfma_f32_16x16x32_bf16 v[64:67], v[196:199], v[228:231], v[64:67]
	v_mfma_f32_16x16x32_bf16 v[112:115], v[192:195], v[208:211], v[112:115]
	v_mfma_f32_16x16x32_bf16 v[104:107], v[200:203], v[208:211], v[104:107]
	v_mfma_f32_16x16x32_bf16 v[96:99], v[192:195], v[216:219], v[96:99]
	v_mfma_f32_16x16x32_bf16 v[88:91], v[200:203], v[216:219], v[88:91]
	v_mfma_f32_16x16x32_bf16 v[80:83], v[192:195], v[224:227], v[80:83]
	v_mfma_f32_16x16x32_bf16 v[72:75], v[200:203], v[224:227], v[72:75]
	v_mfma_f32_16x16x32_bf16 v[68:71], v[192:195], v[232:235], v[68:71]
	v_mfma_f32_16x16x32_bf16 v[64:67], v[200:203], v[232:235], v[64:67]
	s_setprio 0
	s_barrier
; #define PG8_STAGE(bufoff, gbase, voff) do { _Pragma("unroll") for (int _i = 0; _i < 2; ++_i) \
;         __builtin_amdgcn_global_load_lds((const unsigned*)((const char*)(gbase) + (voff)[_i]), (PG8_LAS unsigned*)(lds + (bufoff) + ldsw + _i * 8192), 16, 0, 0); } while (0)
; #define PG8_LDA(dst, b, h) do { _Pragma("unroll") for (int m = 0; m < 4; ++m) _Pragma("unroll") for (int k = 0; k < 2; ++k) dst[m][k] = *(const PG8_LAS bf16x8*)(lds + PG8_SA(b, h) + aoff + m * 2048 + k * 1024); } while (0)
; #define PG8_MMA(ai, bj, At, Bt) do { __builtin_amdgcn_s_setprio(1); _Pragma("unroll") for (int m = 0; m < 4; ++m) _Pragma("unroll") for (int n = 0; n < 2; ++n) _Pragma("unroll") for (int k = 0; k < 2; ++k) \
;         acc[ai][bj][m][n] = __builtin_amdgcn_mfma_f32_16x16x32_bf16(Bt[n][k], At[m][k], acc[ai][bj][m][n], 0, 0, 0); __builtin_amdgcn_s_setprio(0); } while (0)
; #define PG8_WAIT_V(n) asm volatile("s_waitcnt vmcnt(" #n ")" ::: "memory")
; #define PG8_WAIT_L(n) asm volatile("s_waitcnt lgkmcnt(" #n ")" ::: "memory")
; #define PG8_BAR __builtin_amdgcn_s_barrier()
; #define PG8_SCHED __builtin_amdgcn_sched_barrier(0)
; template <class Epi, class Sched, bool ALIGN_EPI = false, bool SP2 = false, bool ABLK = false>
; __device__ __forceinline__ void gemm_phase(PG8_LAS unsigned char* lds, const Gemm g, const Sched& S, const Epi& E) {
;     ...
;         for (int t = 0; t < nt; t += 2) {
;     ...
;             PG8_LDA(At, 1, 1); PG8_STAGE(PG8_SB(1, 0), b3, voffB); PG8_STAGE(PG8_SB(1, 1), b3 + hstep, voffB); PG8_STAGE(PG8_SA(1, 0), a3, voffA);
;             PG8_WAIT_V(8); PG8_WAIT_L(0); PG8_BAR; PG8_MMA(1, 0, At, B0); PG8_MMA(1, 1, At, B1); PG8_BAR; PG8_SCHED;
	s_add_i32 s26, s28, s46
	v_lshl_add_u64 v[176:177], v[176:177], 0, s[52:53]
	s_mov_b32 m0, s26
	ds_read_b128 v[204:207], v165 offset:49152
	ds_read_b128 v[208:211], v165 offset:50176
	ds_read_b128 v[212:215], v165 offset:51200
	ds_read_b128 v[216:219], v165 offset:52224
	ds_read_b128 v[220:223], v165 offset:53248
	ds_read_b128 v[224:227], v165 offset:54272
	ds_read_b128 v[228:231], v165 offset:55296
	ds_read_b128 v[232:235], v165 offset:56320
	global_load_lds_dwordx4 v[176:177], off
	s_add_i32 m0, s26, 0x2000
	s_add_u32 s0, s0, 0x40080
	v_lshl_add_u64 v[176:177], v[236:237], 0, s[52:53]
	s_addc_u32 s1, s1, 0
	s_add_i32 s26, s29, s46
	global_load_lds_dwordx4 v[176:177], off
	v_lshl_add_u64 v[176:177], s[0:1], 0, v[136:137]
	s_mov_b32 m0, s26
	s_nop 0
	global_load_lds_dwordx4 v[176:177], off
	v_lshl_add_u64 v[176:177], s[0:1], 0, v[132:133]
	s_add_i32 m0, s26, 0x2000
	s_nop 0
	global_load_lds_dwordx4 v[176:177], off
	v_lshl_add_u64 v[176:177], v[238:239], 0, s[52:53]
	s_mov_b32 m0, s14
	s_nop 0
	global_load_lds_dwordx4 v[176:177], off
	v_lshl_add_u64 v[176:177], v[240:241], 0, s[52:53]
	s_mov_b32 m0, s15
	s_nop 0
	global_load_lds_dwordx4 v[176:177], off
	s_waitcnt vmcnt(8)
	s_waitcnt lgkmcnt(0)
	s_barrier
	s_setprio 1
	s_waitcnt lgkmcnt(0)
	v_mfma_f32_16x16x32_bf16 v[60:63], v[166:169], v[204:207], v[60:63]
	v_mfma_f32_16x16x32_bf16 v[56:59], v[180:183], v[204:207], v[56:59]
	v_mfma_f32_16x16x32_bf16 v[52:55], v[166:169], v[212:215], v[52:55]
	v_mfma_f32_16x16x32_bf16 v[44:47], v[180:183], v[212:215], v[44:47]
	v_mfma_f32_16x16x32_bf16 v[36:39], v[166:169], v[220:223], v[36:39]
	v_mfma_f32_16x16x32_bf16 v[28:31], v[180:183], v[220:223], v[28:31]
	v_mfma_f32_16x16x32_bf16 v[20:23], v[166:169], v[228:231], v[20:23]
	v_mfma_f32_16x16x32_bf16 v[12:15], v[180:183], v[228:231], v[12:15]
	v_mfma_f32_16x16x32_bf16 v[60:63], v[170:173], v[208:211], v[60:63]
	v_mfma_f32_16x16x32_bf16 v[56:59], v[184:187], v[208:211], v[56:59]
	v_mfma_f32_16x16x32_bf16 v[52:55], v[170:173], v[216:219], v[52:55]
	v_mfma_f32_16x16x32_bf16 v[44:47], v[184:187], v[216:219], v[44:47]
	v_mfma_f32_16x16x32_bf16 v[36:39], v[170:173], v[224:227], v[36:39]
	v_mfma_f32_16x16x32_bf16 v[28:31], v[184:187], v[224:227], v[28:31]
	v_mfma_f32_16x16x32_bf16 v[20:23], v[170:173], v[232:235], v[20:23]
	v_mfma_f32_16x16x32_bf16 v[12:15], v[184:187], v[232:235], v[12:15]
	s_setprio 0
	s_setprio 1
	v_mfma_f32_16x16x32_bf16 v[48:51], v[188:191], v[204:207], v[48:51]
	v_mfma_f32_16x16x32_bf16 v[40:43], v[196:199], v[204:207], v[40:43]
	v_mfma_f32_16x16x32_bf16 v[32:35], v[188:191], v[212:215], v[32:35]
	v_mfma_f32_16x16x32_bf16 v[24:27], v[196:199], v[212:215], v[24:27]
	v_mfma_f32_16x16x32_bf16 v[16:19], v[188:191], v[220:223], v[16:19]
	v_mfma_f32_16x16x32_bf16 v[8:11], v[196:199], v[220:223], v[8:11]
	v_mfma_f32_16x16x32_bf16 v[4:7], v[188:191], v[228:231], v[4:7]
	v_mfma_f32_16x16x32_bf16 v[0:3], v[196:199], v[228:231], v[0:3]
	v_mfma_f32_16x16x32_bf16 v[48:51], v[192:195], v[208:211], v[48:51]
	v_mfma_f32_16x16x32_bf16 v[40:43], v[200:203], v[208:211], v[40:43]
	v_mfma_f32_16x16x32_bf16 v[32:35], v[192:195], v[216:219], v[32:35]
	v_mfma_f32_16x16x32_bf16 v[24:27], v[200:203], v[216:219], v[24:27]
	v_mfma_f32_16x16x32_bf16 v[16:19], v[192:195], v[224:227], v[16:19]
	v_mfma_f32_16x16x32_bf16 v[8:11], v[200:203], v[224:227], v[8:11]
	v_mfma_f32_16x16x32_bf16 v[4:7], v[192:195], v[232:235], v[4:7]
	v_mfma_f32_16x16x32_bf16 v[0:3], v[200:203], v[232:235], v[0:3]
	s_setprio 0
	s_barrier
	s_add_i32 s25, s25, 2
	s_add_u32 vcc_lo, vcc_lo, 0x100
	s_addc_u32 vcc_hi, vcc_hi, 0
	s_add_u32 s23, s23, 0x100
	s_addc_u32 s24, s24, 0
	s_cmp_gt_u32 s25, 13
	s_cbranch_scc0 .LBB0_215
	s_branch .Lp1_kdone

; #define PG8_BAR __builtin_amdgcn_s_barrier()
; template <class Epi, class Sched, bool ALIGN_EPI = false, bool SP2 = false, bool ABLK = false>
; __device__ __forceinline__ void gemm_phase(PG8_LAS unsigned char* lds, const Gemm g, const Sched& S, const Epi& E) {
;     ...
;         if constexpr (ALIGN_EPI) { if (wr == 0) PG8_BAR; }
.Lp1_kdone:
	s_and_b64 vcc, exec, s[92:93]
	s_cbranch_vccz .LBB0_218
	s_barrier

; #define PG8_STAGE(bufoff, gbase, voff) do { _Pragma("unroll") for (int _i = 0; _i < 2; ++_i) \
;         __builtin_amdgcn_global_load_lds((const unsigned*)((const char*)(gbase) + (voff)[_i]), (PG8_LAS unsigned*)(lds + (bufoff) + ldsw + _i * 8192), 16, 0, 0); } while (0)
; #define PG8_LDA(dst, b, h) do { _Pragma("unroll") for (int m = 0; m < 4; ++m) _Pragma("unroll") for (int k = 0; k < 2; ++k) dst[m][k] = *(const PG8_LAS bf16x8*)(lds + PG8_SA(b, h) + aoff + m * 2048 + k * 1024); } while (0)
; #define PG8_LDB(dst, b, h) do { _Pragma("unroll") for (int n = 0; n < 2; ++n) _Pragma("unroll") for (int k = 0; k < 2; ++k) dst[n][k] = *(const PG8_LAS bf16x8*)(lds + PG8_SB(b, h) + boff + n * 2048 + k * 1024); } while (0)
; #define PG8_WAIT_V(n) asm volatile("s_waitcnt vmcnt(" #n ")" ::: "memory")
; #define PG8_WAIT_L(n) asm volatile("s_waitcnt lgkmcnt(" #n ")" ::: "memory")
; #define PG8_BAR __builtin_amdgcn_s_barrier()
; template <class Epi, class Sched, bool ALIGN_EPI = false, bool SP2 = false, bool ABLK = false>
; __device__ __forceinline__ void gemm_phase(PG8_LAS unsigned char* lds, const Gemm g, const Sched& S, const Epi& E) {
;     ...
;         const char* nA = has_next ? (const char*)g.A + (size_t)nxt.pm * tstepA : cA; const char* nB = has_next ? (const char*)g.Bt + (size_t)nxt.pn * tstep : cB;
;         for (int t = 0; t < nt; t += 2) {
;             if constexpr (Epi::MID) { if (t == nt / 2) E.mid(acc, cur, wr, wc, fr, fq); }
;             const bool last = (t == nt - 2);
;             const char* a1 = cA + (size_t)(t + 1) * kstepA;
;             const char* a2 = last ? nA : cA + (size_t)(t + 2) * kstepA; const char* b2 = last ? nB : cB + (size_t)(t + 2) * kstep;
;             const char* a3 = a2 + kstepA; const char* b3 = b2 + kstep;
;             if (last && has_next) S.a_ready(nxt);
;             if constexpr (SP2) {
;             PG8_LDB(B0, 0, 0); PG8_LDB(B1, 0, 1); PG8_SCHED; PG8_LDA(At, 0, 0); PG8_STAGE(PG8_SA(1, 1), a1 + hstepA, voffA);
;             PG8_WAIT_V(8); PG8_WAIT_L(0); PG8_BAR; PG8_MMA(0, 0, At, B0); PG8_MMA(0, 1, At, B1); PG8_BAR; PG8_SCHED;
;             PG8_LDA(At, 0, 1); PG8_STAGE(PG8_SB(0, 0), b2, voffB); PG8_STAGE(PG8_SB(0, 1), b2 + hstep, voffB); PG8_STAGE(PG8_SA(0, 0), a2, voffA);
;             PG8_WAIT_V(8); PG8_WAIT_L(0); PG8_BAR; PG8_MMA(1, 0, At, B0); PG8_MMA(1, 1, At, B1); PG8_BAR; PG8_SCHED;
.LBB0_533:
	s_ashr_i32 s21, s20, 31
	s_lshl_b64 s[8:9], s[20:21], 19
	s_add_u32 s24, s10, s8
	s_addc_u32 s25, s11, s9
	s_and_b64 s[8:9], s[26:27], exec
	s_cselect_b32 s7, s25, s37
	s_cselect_b32 s21, s24, s36
	s_ashr_i32 s23, s22, 31
	s_lshl_b64 s[8:9], s[22:23], 19
	s_add_u32 s28, s52, s8
	s_addc_u32 s29, s53, s9
	s_and_b64 s[8:9], s[26:27], exec
	s_cselect_b32 s23, s29, s35
	s_cselect_b32 s31, s28, s34
	s_add_u32 s61, s34, 0x100
	s_addc_u32 s62, s35, 0
	s_add_u32 s8, s36, 0xc000
	s_addc_u32 s9, s37, 0
	s_mov_b32 s63, -2
	ds_read_b128 v[128:131], v143
	ds_read_b128 v[176:179], v143 offset:1024
	ds_read_b128 v[180:183], v143 offset:2048
	ds_read_b128 v[184:187], v143 offset:3072
	ds_read_b128 v[188:191], v167
	ds_read_b128 v[192:195], v167 offset:1024
	ds_read_b128 v[196:199], v167 offset:2048
	ds_read_b128 v[200:203], v167 offset:3072
	s_add_u32 s2, s8, 0x4000
	s_addc_u32 s34, s9, 0
	s_cmp_eq_u32 s63, 12
	s_cselect_b32 s38, s21, s2
	s_cselect_b32 s39, s7, s34
	s_cselect_b32 s36, s31, s61
	s_cselect_b32 s37, s23, s62
	s_add_u32 s34, s38, 0x8000
	s_addc_u32 s35, s39, 0
	s_mov_b32 m0, s58
	v_lshl_add_u64 v[172:173], s[8:9], 0, v[162:163]
	ds_read_b128 v[204:207], v168
	ds_read_b128 v[208:211], v168 offset:1024
	ds_read_b128 v[212:215], v168 offset:2048
	ds_read_b128 v[216:219], v168 offset:3072
	ds_read_b128 v[220:223], v168 offset:4096
	ds_read_b128 v[224:227], v168 offset:5120
	ds_read_b128 v[228:231], v168 offset:6144
	ds_read_b128 v[232:235], v168 offset:7168
	global_load_lds_dwordx4 v[172:173], off
	v_lshl_add_u64 v[172:173], s[8:9], 0, v[164:165]
	s_mov_b32 m0, s59
	s_nop 0
	global_load_lds_dwordx4 v[172:173], off
	s_waitcnt vmcnt(8)
	s_waitcnt lgkmcnt(0)
	s_barrier
	s_setprio 1
	s_waitcnt lgkmcnt(0)
	v_mfma_f32_16x16x32_bf16 v[124:127], v[128:131], v[204:207], 0
	v_mfma_f32_16x16x32_bf16 v[120:123], v[180:183], v[204:207], 0
	v_mfma_f32_16x16x32_bf16 v[108:111], v[128:131], v[212:215], 0
	v_mfma_f32_16x16x32_bf16 v[104:107], v[180:183], v[212:215], 0
	v_mfma_f32_16x16x32_bf16 v[92:95], v[128:131], v[220:223], 0
	v_mfma_f32_16x16x32_bf16 v[88:91], v[180:183], v[220:223], 0
	v_mfma_f32_16x16x32_bf16 v[76:79], v[128:131], v[228:231], 0
	v_mfma_f32_16x16x32_bf16 v[72:75], v[180:183], v[228:231], 0
	v_mfma_f32_16x16x32_bf16 v[124:127], v[176:179], v[208:211], v[124:127]
	v_mfma_f32_16x16x32_bf16 v[120:123], v[184:187], v[208:211], v[120:123]
	v_mfma_f32_16x16x32_bf16 v[108:111], v[176:179], v[216:219], v[108:111]
	v_mfma_f32_16x16x32_bf16 v[104:107], v[184:187], v[216:219], v[104:107]
	v_mfma_f32_16x16x32_bf16 v[92:95], v[176:179], v[224:227], v[92:95]
	v_mfma_f32_16x16x32_bf16 v[88:91], v[184:187], v[224:227], v[88:91]
	v_mfma_f32_16x16x32_bf16 v[76:79], v[176:179], v[232:235], v[76:79]
	v_mfma_f32_16x16x32_bf16 v[72:75], v[184:187], v[232:235], v[72:75]
	s_setprio 0
	s_setprio 1
	v_mfma_f32_16x16x32_bf16 v[116:119], v[188:191], v[204:207], 0
	v_mfma_f32_16x16x32_bf16 v[112:115], v[196:199], v[204:207], 0
	v_mfma_f32_16x16x32_bf16 v[100:103], v[188:191], v[212:215], 0
	v_mfma_f32_16x16x32_bf16 v[96:99], v[196:199], v[212:215], 0
	v_mfma_f32_16x16x32_bf16 v[84:87], v[188:191], v[220:223], 0
	v_mfma_f32_16x16x32_bf16 v[80:83], v[196:199], v[220:223], 0
	v_mfma_f32_16x16x32_bf16 v[68:71], v[188:191], v[228:231], 0
	v_mfma_f32_16x16x32_bf16 v[64:67], v[196:199], v[228:231], 0
	v_mfma_f32_16x16x32_bf16 v[116:119], v[192:195], v[208:211], v[116:119]
	v_mfma_f32_16x16x32_bf16 v[112:115], v[200:203], v[208:211], v[112:115]
	v_mfma_f32_16x16x32_bf16 v[100:103], v[192:195], v[216:219], v[100:103]
	v_mfma_f32_16x16x32_bf16 v[96:99], v[200:203], v[216:219], v[96:99]
	v_mfma_f32_16x16x32_bf16 v[84:87], v[192:195], v[224:227], v[84:87]
	v_mfma_f32_16x16x32_bf16 v[80:83], v[200:203], v[224:227], v[80:83]
	v_mfma_f32_16x16x32_bf16 v[68:71], v[192:195], v[232:235], v[68:71]
	v_mfma_f32_16x16x32_bf16 v[64:67], v[200:203], v[232:235], v[64:67]
	s_setprio 0
	s_barrier
	s_mov_b32 m0, s60
	v_lshl_add_u64 v[172:173], s[36:37], 0, v[136:137]
	ds_read_b128 v[204:207], v168 offset:16384
	ds_read_b128 v[208:211], v168 offset:17408
	ds_read_b128 v[212:215], v168 offset:18432
	ds_read_b128 v[216:219], v168 offset:19456
	ds_read_b128 v[220:223], v168 offset:20480
	ds_read_b128 v[224:227], v168 offset:21504
	ds_read_b128 v[228:231], v168 offset:22528
	ds_read_b128 v[232:235], v168 offset:23552
	global_load_lds_dwordx4 v[172:173], off
	s_add_i32 m0, s60, 0x2000
	s_add_u32 s70, s36, 0x40000
	v_lshl_add_u64 v[236:237], s[36:37], 0, v[132:133]
	s_addc_u32 s71, s37, 0
	s_add_i32 s2, s57, s3
	global_load_lds_dwordx4 v[236:237], off
	v_lshl_add_u64 v[238:239], s[70:71], 0, v[136:137]
	s_mov_b32 m0, s2
	s_nop 0
	global_load_lds_dwordx4 v[238:239], off
	v_lshl_add_u64 v[238:239], s[70:71], 0, v[132:133]
	s_add_i32 m0, s2, 0x2000
	s_nop 0
	global_load_lds_dwordx4 v[238:239], off
	v_lshl_add_u64 v[238:239], s[38:39], 0, v[138:139]
	s_mov_b32 m0, s40
	s_nop 0
	global_load_lds_dwordx4 v[238:239], off
	v_lshl_add_u64 v[238:239], s[38:39], 0, v[134:135]
	s_mov_b32 m0, s41
	s_nop 0
	global_load_lds_dwordx4 v[238:239], off
	s_waitcnt vmcnt(8)
	s_waitcnt lgkmcnt(0)
	s_barrier
; #define PG8_STAGE(bufoff, gbase, voff) do { _Pragma("unroll") for (int _i = 0; _i < 2; ++_i) \
;         __builtin_amdgcn_global_load_lds((const unsigned*)((const char*)(gbase) + (voff)[_i]), (PG8_LAS unsigned*)(lds + (bufoff) + ldsw + _i * 8192), 16, 0, 0); } while (0)
; #define PG8_LDA(dst, b, h) do { _Pragma("unroll") for (int m = 0; m < 4; ++m) _Pragma("unroll") for (int k = 0; k < 2; ++k) dst[m][k] = *(const PG8_LAS bf16x8*)(lds + PG8_SA(b, h) + aoff + m * 2048 + k * 1024); } while (0)
; #define PG8_LDB(dst, b, h) do { _Pragma("unroll") for (int n = 0; n < 2; ++n) _Pragma("unroll") for (int k = 0; k < 2; ++k) dst[n][k] = *(const PG8_LAS bf16x8*)(lds + PG8_SB(b, h) + boff + n * 2048 + k * 1024); } while (0)
; #define PG8_MMA(ai, bj, At, Bt) do { __builtin_amdgcn_s_setprio(1); _Pragma("unroll") for (int m = 0; m < 4; ++m) _Pragma("unroll") for (int n = 0; n < 2; ++n) _Pragma("unroll") for (int k = 0; k < 2; ++k) \
;         acc[ai][bj][m][n] = __builtin_amdgcn_mfma_f32_16x16x32_bf16(Bt[n][k], At[m][k], acc[ai][bj][m][n], 0, 0, 0); __builtin_amdgcn_s_setprio(0); } while (0)
; #define PG8_WAIT_V(n) asm volatile("s_waitcnt vmcnt(" #n ")" ::: "memory")
; #define PG8_WAIT_L(n) asm volatile("s_waitcnt lgkmcnt(" #n ")" ::: "memory")
; #define PG8_BAR __builtin_amdgcn_s_barrier()
; #define PG8_SCHED __builtin_amdgcn_sched_barrier(0)
; template <class Epi, class Sched, bool ALIGN_EPI = false, bool SP2 = false, bool ABLK = false>
; __device__ __forceinline__ void gemm_phase(PG8_LAS unsigned char* lds, const Gemm g, const Sched& S, const Epi& E) {
;     ...
;             PG8_WAIT_V(8); PG8_WAIT_L(0); PG8_BAR; PG8_MMA(1, 0, At, B0); PG8_MMA(1, 1, At, B1); PG8_BAR; PG8_SCHED;
;             PG8_LDB(B0, 1, 0); PG8_LDB(B1, 1, 1); PG8_SCHED; PG8_LDA(At, 1, 0); PG8_STAGE(PG8_SA(0, 1), a2 + hstepA, voffA);
;             PG8_WAIT_V(8); PG8_WAIT_L(0); PG8_BAR; PG8_MMA(0, 0, At, B0); PG8_MMA(0, 1, At, B1); PG8_BAR; PG8_SCHED;
	s_setprio 1
	s_waitcnt lgkmcnt(0)
	v_mfma_f32_16x16x32_bf16 v[60:63], v[128:131], v[204:207], 0
	v_mfma_f32_16x16x32_bf16 v[56:59], v[180:183], v[204:207], 0
	v_mfma_f32_16x16x32_bf16 v[44:47], v[128:131], v[212:215], 0
	v_mfma_f32_16x16x32_bf16 v[40:43], v[180:183], v[212:215], 0
	v_mfma_f32_16x16x32_bf16 v[28:31], v[128:131], v[220:223], 0
	v_mfma_f32_16x16x32_bf16 v[24:27], v[180:183], v[220:223], 0
	v_mfma_f32_16x16x32_bf16 v[12:15], v[128:131], v[228:231], 0
	v_mfma_f32_16x16x32_bf16 v[8:11], v[180:183], v[228:231], 0
	v_mfma_f32_16x16x32_bf16 v[60:63], v[176:179], v[208:211], v[60:63]
	v_mfma_f32_16x16x32_bf16 v[56:59], v[184:187], v[208:211], v[56:59]
	v_mfma_f32_16x16x32_bf16 v[44:47], v[176:179], v[216:219], v[44:47]
	v_mfma_f32_16x16x32_bf16 v[40:43], v[184:187], v[216:219], v[40:43]
	v_mfma_f32_16x16x32_bf16 v[28:31], v[176:179], v[224:227], v[28:31]
	v_mfma_f32_16x16x32_bf16 v[24:27], v[184:187], v[224:227], v[24:27]
	v_mfma_f32_16x16x32_bf16 v[12:15], v[176:179], v[232:235], v[12:15]
	v_mfma_f32_16x16x32_bf16 v[8:11], v[184:187], v[232:235], v[8:11]
	s_setprio 0
	s_setprio 1
	v_mfma_f32_16x16x32_bf16 v[52:55], v[188:191], v[204:207], 0
	v_mfma_f32_16x16x32_bf16 v[48:51], v[196:199], v[204:207], 0
	v_mfma_f32_16x16x32_bf16 v[36:39], v[188:191], v[212:215], 0
	v_mfma_f32_16x16x32_bf16 v[32:35], v[196:199], v[212:215], 0
	v_mfma_f32_16x16x32_bf16 v[20:23], v[188:191], v[220:223], 0
	v_mfma_f32_16x16x32_bf16 v[16:19], v[196:199], v[220:223], 0
	v_mfma_f32_16x16x32_bf16 v[4:7], v[188:191], v[228:231], 0
	v_mfma_f32_16x16x32_bf16 v[0:3], v[196:199], v[228:231], 0
	v_mfma_f32_16x16x32_bf16 v[52:55], v[192:195], v[208:211], v[52:55]
	v_mfma_f32_16x16x32_bf16 v[48:51], v[200:203], v[208:211], v[48:51]
	v_mfma_f32_16x16x32_bf16 v[36:39], v[192:195], v[216:219], v[36:39]
	v_mfma_f32_16x16x32_bf16 v[32:35], v[200:203], v[216:219], v[32:35]
	v_mfma_f32_16x16x32_bf16 v[20:23], v[192:195], v[224:227], v[20:23]
	v_mfma_f32_16x16x32_bf16 v[16:19], v[200:203], v[224:227], v[16:19]
	v_mfma_f32_16x16x32_bf16 v[4:7], v[192:195], v[232:235], v[4:7]
	v_mfma_f32_16x16x32_bf16 v[0:3], v[200:203], v[232:235], v[0:3]
	s_setprio 0
	s_barrier
	s_add_i32 s2, 0, 0x18000
	v_add_u32_e32 v171, s2, v166
	s_add_i32 s70, 0, 0x1c000
	ds_read_b128 v[128:131], v171
	ds_read_b128 v[176:179], v171 offset:1024
	ds_read_b128 v[180:183], v171 offset:2048
	ds_read_b128 v[184:187], v171 offset:3072
	v_add_u32_e32 v171, s70, v166
	ds_read_b128 v[188:191], v171
	ds_read_b128 v[192:195], v171 offset:1024
	ds_read_b128 v[196:199], v171 offset:2048
	ds_read_b128 v[200:203], v171 offset:3072
	s_add_u32 s38, s38, 0x4000
	s_addc_u32 s39, s39, 0
	s_mov_b32 m0, s44
	v_lshl_add_u64 v[238:239], s[38:39], 0, v[138:139]
	ds_read_b128 v[204:207], v168 offset:32768
	ds_read_b128 v[208:211], v168 offset:33792
	ds_read_b128 v[212:215], v168 offset:34816
	ds_read_b128 v[216:219], v168 offset:35840
	ds_read_b128 v[220:223], v168 offset:36864
	ds_read_b128 v[224:227], v168 offset:37888
	ds_read_b128 v[228:231], v168 offset:38912
	ds_read_b128 v[232:235], v168 offset:39936
	global_load_lds_dwordx4 v[238:239], off
	v_lshl_add_u64 v[238:239], s[38:39], 0, v[134:135]
	s_mov_b32 m0, s45
	s_nop 0
	global_load_lds_dwordx4 v[238:239], off
	s_waitcnt vmcnt(8)
	s_waitcnt lgkmcnt(0)
	s_barrier
	s_setprio 1
	s_waitcnt lgkmcnt(0)
	v_mfma_f32_16x16x32_bf16 v[124:127], v[128:131], v[204:207], v[124:127]
	v_mfma_f32_16x16x32_bf16 v[120:123], v[180:183], v[204:207], v[120:123]
	v_mfma_f32_16x16x32_bf16 v[108:111], v[128:131], v[212:215], v[108:111]
	v_mfma_f32_16x16x32_bf16 v[104:107], v[180:183], v[212:215], v[104:107]
	v_mfma_f32_16x16x32_bf16 v[92:95], v[128:131], v[220:223], v[92:95]
	v_mfma_f32_16x16x32_bf16 v[88:91], v[180:183], v[220:223], v[88:91]
	v_mfma_f32_16x16x32_bf16 v[76:79], v[128:131], v[228:231], v[76:79]
	v_mfma_f32_16x16x32_bf16 v[72:75], v[180:183], v[228:231], v[72:75]
	v_mfma_f32_16x16x32_bf16 v[124:127], v[176:179], v[208:211], v[124:127]
	v_mfma_f32_16x16x32_bf16 v[120:123], v[184:187], v[208:211], v[120:123]
	v_mfma_f32_16x16x32_bf16 v[108:111], v[176:179], v[216:219], v[108:111]
	v_mfma_f32_16x16x32_bf16 v[104:107], v[184:187], v[216:219], v[104:107]
	v_mfma_f32_16x16x32_bf16 v[92:95], v[176:179], v[224:227], v[92:95]
	v_mfma_f32_16x16x32_bf16 v[88:91], v[184:187], v[224:227], v[88:91]
	v_mfma_f32_16x16x32_bf16 v[76:79], v[176:179], v[232:235], v[76:79]
	v_mfma_f32_16x16x32_bf16 v[72:75], v[184:187], v[232:235], v[72:75]
	s_setprio 0
	s_setprio 1
	v_mfma_f32_16x16x32_bf16 v[116:119], v[188:191], v[204:207], v[116:119]
	v_mfma_f32_16x16x32_bf16 v[112:115], v[196:199], v[204:207], v[112:115]
	v_mfma_f32_16x16x32_bf16 v[100:103], v[188:191], v[212:215], v[100:103]
	v_mfma_f32_16x16x32_bf16 v[96:99], v[196:199], v[212:215], v[96:99]
	v_mfma_f32_16x16x32_bf16 v[84:87], v[188:191], v[220:223], v[84:87]
	v_mfma_f32_16x16x32_bf16 v[80:83], v[196:199], v[220:223], v[80:83]
	v_mfma_f32_16x16x32_bf16 v[68:71], v[188:191], v[228:231], v[68:71]
	v_mfma_f32_16x16x32_bf16 v[64:67], v[196:199], v[228:231], v[64:67]
	v_mfma_f32_16x16x32_bf16 v[116:119], v[192:195], v[208:211], v[116:119]
	v_mfma_f32_16x16x32_bf16 v[112:115], v[200:203], v[208:211], v[112:115]
	v_mfma_f32_16x16x32_bf16 v[100:103], v[192:195], v[216:219], v[100:103]
	v_mfma_f32_16x16x32_bf16 v[96:99], v[200:203], v[216:219], v[96:99]
	v_mfma_f32_16x16x32_bf16 v[84:87], v[192:195], v[224:227], v[84:87]
	v_mfma_f32_16x16x32_bf16 v[80:83], v[200:203], v[224:227], v[80:83]
	v_mfma_f32_16x16x32_bf16 v[68:71], v[192:195], v[232:235], v[68:71]
	v_mfma_f32_16x16x32_bf16 v[64:67], v[200:203], v[232:235], v[64:67]
	s_setprio 0
	s_barrier
; #define PG8_STAGE(bufoff, gbase, voff) do { _Pragma("unroll") for (int _i = 0; _i < 2; ++_i) \
;         __builtin_amdgcn_global_load_lds((const unsigned*)((const char*)(gbase) + (voff)[_i]), (PG8_LAS unsigned*)(lds + (bufoff) + ldsw + _i * 8192), 16, 0, 0); } while (0)
; #define PG8_LDA(dst, b, h) do { _Pragma("unroll") for (int m = 0; m < 4; ++m) _Pragma("unroll") for (int k = 0; k < 2; ++k) dst[m][k] = *(const PG8_LAS bf16x8*)(lds + PG8_SA(b, h) + aoff + m * 2048 + k * 1024); } while (0)
; #define PG8_MMA(ai, bj, At, Bt) do { __builtin_amdgcn_s_setprio(1); _Pragma("unroll") for (int m = 0; m < 4; ++m) _Pragma("unroll") for (int n = 0; n < 2; ++n) _Pragma("unroll") for (int k = 0; k < 2; ++k) \
;         acc[ai][bj][m][n] = __builtin_amdgcn_mfma_f32_16x16x32_bf16(Bt[n][k], At[m][k], acc[ai][bj][m][n], 0, 0, 0); __builtin_amdgcn_s_setprio(0); } while (0)
; #define PG8_WAIT_V(n) asm volatile("s_waitcnt vmcnt(" #n ")" ::: "memory")
; #define PG8_WAIT_L(n) asm volatile("s_waitcnt lgkmcnt(" #n ")" ::: "memory")
; #define PG8_BAR __builtin_amdgcn_s_barrier()
; #define PG8_SCHED __builtin_amdgcn_sched_barrier(0)
; template <class Epi, class Sched, bool ALIGN_EPI = false, bool SP2 = false, bool ABLK = false>
; __device__ __forceinline__ void gemm_phase(PG8_LAS unsigned char* lds, const Gemm g, const Sched& S, const Epi& E) {
;     ...
;         for (int t = 0; t < nt; t += 2) {
;     ...
;             PG8_LDA(At, 1, 1); PG8_STAGE(PG8_SB(1, 0), b3, voffB); PG8_STAGE(PG8_SB(1, 1), b3 + hstep, voffB); PG8_STAGE(PG8_SA(1, 0), a3, voffA);
;             PG8_WAIT_V(8); PG8_WAIT_L(0); PG8_BAR; PG8_MMA(1, 0, At, B0); PG8_MMA(1, 1, At, B1); PG8_BAR; PG8_SCHED;
	s_add_i32 s2, s2, s3
	v_lshl_add_u64 v[172:173], v[172:173], 0, s[16:17]
	s_mov_b32 m0, s2
	ds_read_b128 v[204:207], v168 offset:49152
	ds_read_b128 v[208:211], v168 offset:50176
	ds_read_b128 v[212:215], v168 offset:51200
	ds_read_b128 v[216:219], v168 offset:52224
	ds_read_b128 v[220:223], v168 offset:53248
	ds_read_b128 v[224:227], v168 offset:54272
	ds_read_b128 v[228:231], v168 offset:55296
	ds_read_b128 v[232:235], v168 offset:56320
	global_load_lds_dwordx4 v[172:173], off
	s_add_i32 m0, s2, 0x2000
	s_add_u32 s36, s36, 0x40080
	v_lshl_add_u64 v[172:173], v[236:237], 0, s[16:17]
	s_addc_u32 s37, s37, 0
	s_add_i32 s2, s70, s3
	global_load_lds_dwordx4 v[172:173], off
	v_lshl_add_u64 v[172:173], s[36:37], 0, v[136:137]
	s_mov_b32 m0, s2
	s_nop 0
	global_load_lds_dwordx4 v[172:173], off
	v_lshl_add_u64 v[172:173], s[36:37], 0, v[132:133]
	s_add_i32 m0, s2, 0x2000
	s_nop 0
	global_load_lds_dwordx4 v[172:173], off
	v_lshl_add_u64 v[172:173], s[34:35], 0, v[138:139]
	s_mov_b32 m0, s55
	s_nop 0
	global_load_lds_dwordx4 v[172:173], off
	v_lshl_add_u64 v[172:173], s[34:35], 0, v[134:135]
	s_mov_b32 m0, s56
	s_nop 0
	global_load_lds_dwordx4 v[172:173], off
	s_waitcnt vmcnt(8)
	s_waitcnt lgkmcnt(0)
	s_barrier
	s_setprio 1
	s_waitcnt lgkmcnt(0)
	v_mfma_f32_16x16x32_bf16 v[60:63], v[128:131], v[204:207], v[60:63]
	v_mfma_f32_16x16x32_bf16 v[56:59], v[180:183], v[204:207], v[56:59]
	v_mfma_f32_16x16x32_bf16 v[44:47], v[128:131], v[212:215], v[44:47]
	v_mfma_f32_16x16x32_bf16 v[40:43], v[180:183], v[212:215], v[40:43]
	v_mfma_f32_16x16x32_bf16 v[28:31], v[128:131], v[220:223], v[28:31]
	v_mfma_f32_16x16x32_bf16 v[24:27], v[180:183], v[220:223], v[24:27]
	v_mfma_f32_16x16x32_bf16 v[12:15], v[128:131], v[228:231], v[12:15]
	v_mfma_f32_16x16x32_bf16 v[8:11], v[180:183], v[228:231], v[8:11]
	v_mfma_f32_16x16x32_bf16 v[60:63], v[176:179], v[208:211], v[60:63]
	v_mfma_f32_16x16x32_bf16 v[56:59], v[184:187], v[208:211], v[56:59]
	v_mfma_f32_16x16x32_bf16 v[44:47], v[176:179], v[216:219], v[44:47]
	v_mfma_f32_16x16x32_bf16 v[40:43], v[184:187], v[216:219], v[40:43]
	v_mfma_f32_16x16x32_bf16 v[28:31], v[176:179], v[224:227], v[28:31]
	v_mfma_f32_16x16x32_bf16 v[24:27], v[184:187], v[224:227], v[24:27]
	v_mfma_f32_16x16x32_bf16 v[12:15], v[176:179], v[232:235], v[12:15]
	v_mfma_f32_16x16x32_bf16 v[8:11], v[184:187], v[232:235], v[8:11]
	s_setprio 0
	s_setprio 1
	v_mfma_f32_16x16x32_bf16 v[52:55], v[188:191], v[204:207], v[52:55]
	v_mfma_f32_16x16x32_bf16 v[48:51], v[196:199], v[204:207], v[48:51]
	v_mfma_f32_16x16x32_bf16 v[36:39], v[188:191], v[212:215], v[36:39]
	v_mfma_f32_16x16x32_bf16 v[32:35], v[196:199], v[212:215], v[32:35]
	v_mfma_f32_16x16x32_bf16 v[20:23], v[188:191], v[220:223], v[20:23]
	v_mfma_f32_16x16x32_bf16 v[16:19], v[196:199], v[220:223], v[16:19]
	v_mfma_f32_16x16x32_bf16 v[4:7], v[188:191], v[228:231], v[4:7]
	v_mfma_f32_16x16x32_bf16 v[0:3], v[196:199], v[228:231], v[0:3]
	v_mfma_f32_16x16x32_bf16 v[52:55], v[192:195], v[208:211], v[52:55]
	v_mfma_f32_16x16x32_bf16 v[48:51], v[200:203], v[208:211], v[48:51]
	v_mfma_f32_16x16x32_bf16 v[36:39], v[192:195], v[216:219], v[36:39]
	v_mfma_f32_16x16x32_bf16 v[32:35], v[200:203], v[216:219], v[32:35]
	v_mfma_f32_16x16x32_bf16 v[20:23], v[192:195], v[224:227], v[20:23]
	v_mfma_f32_16x16x32_bf16 v[16:19], v[200:203], v[224:227], v[16:19]
	v_mfma_f32_16x16x32_bf16 v[4:7], v[192:195], v[232:235], v[4:7]
	v_mfma_f32_16x16x32_bf16 v[0:3], v[200:203], v[232:235], v[0:3]
	s_setprio 0
	s_barrier
	s_add_i32 s63, s63, 2
	s_add_u32 s61, s61, 0x100
	s_addc_u32 s62, s62, 0
	s_add_u32 s8, s8, 0x10000
	s_addc_u32 s9, s9, 0
	s_cmp_gt_u32 s63, 13
	s_cbranch_scc0 .LBB0_534
	s_branch .Lp4_kdone

; #define PG8_BAR __builtin_amdgcn_s_barrier()
; template <class Epi, class Sched, bool ALIGN_EPI = false, bool SP2 = false, bool ABLK = false>
; __device__ __forceinline__ void gemm_phase(PG8_LAS unsigned char* lds, const Gemm g, const Sched& S, const Epi& E) {
;     ...
;         if constexpr (ALIGN_EPI) { if (wr == 0) PG8_BAR; }
.Lp4_kdone:
	s_and_b64 vcc, exec, s[18:19]
	s_cbranch_vccz .LBB0_537
	s_barrier

; #define PG8_STAGE(bufoff, gbase, voff) do { _Pragma("unroll") for (int _i = 0; _i < 2; ++_i) \
;         __builtin_amdgcn_global_load_lds((const unsigned*)((const char*)(gbase) + (voff)[_i]), (PG8_LAS unsigned*)(lds + (bufoff) + ldsw + _i * 8192), 16, 0, 0); } while (0)
; #define PG8_LDA(dst, b, h) do { _Pragma("unroll") for (int m = 0; m < 4; ++m) _Pragma("unroll") for (int k = 0; k < 2; ++k) dst[m][k] = *(const PG8_LAS bf16x8*)(lds + PG8_SA(b, h) + aoff + m * 2048 + k * 1024); } while (0)
; #define PG8_LDB(dst, b, h) do { _Pragma("unroll") for (int n = 0; n < 2; ++n) _Pragma("unroll") for (int k = 0; k < 2; ++k) dst[n][k] = *(const PG8_LAS bf16x8*)(lds + PG8_SB(b, h) + boff + n * 2048 + k * 1024); } while (0)
; #define PG8_WAIT_V(n) asm volatile("s_waitcnt vmcnt(" #n ")" ::: "memory")
; #define PG8_WAIT_L(n) asm volatile("s_waitcnt lgkmcnt(" #n ")" ::: "memory")
; #define PG8_BAR __builtin_amdgcn_s_barrier()
; template <class Epi, class Sched, bool ALIGN_EPI = false, bool SP2 = false, bool ABLK = false>
; __device__ __forceinline__ void gemm_phase(PG8_LAS unsigned char* lds, const Gemm g, const Sched& S, const Epi& E) {
;     ...
;         const char* nA = has_next ? (const char*)g.A + (size_t)nxt.pm * tstepA : cA; const char* nB = has_next ? (const char*)g.Bt + (size_t)nxt.pn * tstep : cB;
;         for (int t = 0; t < nt; t += 2) {
;             if constexpr (Epi::MID) { if (t == nt / 2) E.mid(acc, cur, wr, wc, fr, fq); }
;             const bool last = (t == nt - 2);
;             const char* a1 = cA + (size_t)(t + 1) * kstepA;
;             const char* a2 = last ? nA : cA + (size_t)(t + 2) * kstepA; const char* b2 = last ? nB : cB + (size_t)(t + 2) * kstep;
;             const char* a3 = a2 + kstepA; const char* b3 = b2 + kstep;
;             if (last && has_next) S.a_ready(nxt);
;             if constexpr (SP2) {
;             PG8_LDB(B0, 0, 0); PG8_LDB(B1, 0, 1); PG8_SCHED; PG8_LDA(At, 0, 0); PG8_STAGE(PG8_SA(1, 1), a1 + hstepA, voffA);
;             PG8_WAIT_V(8); PG8_WAIT_L(0); PG8_BAR; PG8_MMA(0, 0, At, B0); PG8_MMA(0, 1, At, B1); PG8_BAR; PG8_SCHED;
;             PG8_LDA(At, 0, 1); PG8_STAGE(PG8_SB(0, 0), b2, voffB); PG8_STAGE(PG8_SB(0, 1), b2 + hstep, voffB); PG8_STAGE(PG8_SA(0, 0), a2, voffA);
;             PG8_WAIT_V(8); PG8_WAIT_L(0); PG8_BAR; PG8_MMA(1, 0, At, B0); PG8_MMA(1, 1, At, B1); PG8_BAR; PG8_SCHED;
.LBB0_577:
	s_ashr_i32 s21, s20, 31
	s_lshl_b64 s[24:25], s[20:21], 21
	s_add_u32 s24, s42, s24
	s_addc_u32 s25, s43, s25
	s_and_b64 s[28:29], s[26:27], exec
	s_cselect_b32 s21, s25, s37
	s_cselect_b32 s31, s24, s36
	s_ashr_i32 s23, s22, 31
	s_lshl_b64 s[28:29], s[22:23], 21
	s_add_u32 s28, s50, s28
	s_addc_u32 s29, s51, s29
	s_and_b64 s[38:39], s[26:27], exec
	s_cselect_b32 s23, s29, s35
	s_cselect_b32 s61, s28, s34
	s_add_u32 s62, s34, 0x100
	s_addc_u32 s63, s35, 0
	s_add_u32 s34, s36, 0xc000
	s_addc_u32 s35, s37, 0
	s_mov_b32 s64, -2
	ds_read_b128 v[142:145], v151
	ds_read_b128 v[154:157], v151 offset:1024
	ds_read_b128 v[158:161], v151 offset:2048
	ds_read_b128 v[162:165], v151 offset:3072
	ds_read_b128 v[166:169], v152
	ds_read_b128 v[170:173], v152 offset:1024
	ds_read_b128 v[174:177], v152 offset:2048
	ds_read_b128 v[178:181], v152 offset:3072
	s_add_u32 s36, s34, 0x4000
	s_addc_u32 s37, s35, 0
	s_cmp_eq_u32 s64, 60
	s_cselect_b32 s40, s31, s36
	s_cselect_b32 s41, s21, s37
	s_cselect_b32 s38, s61, s62
	s_cselect_b32 s39, s23, s63
	s_add_u32 s36, s40, 0x8000
	s_addc_u32 s37, s41, 0
	v_lshl_add_u64 v[146:147], s[34:35], 0, v[138:139]
	s_add_i32 m0, s45, 0xc000
	ds_read_b128 v[182:185], v153
	ds_read_b128 v[186:189], v153 offset:1024
	ds_read_b128 v[190:193], v153 offset:2048
	ds_read_b128 v[194:197], v153 offset:3072
	ds_read_b128 v[198:201], v153 offset:4096
	ds_read_b128 v[202:205], v153 offset:5120
	ds_read_b128 v[206:209], v153 offset:6144
	ds_read_b128 v[210:213], v153 offset:7168
	global_load_lds_dwordx4 v[146:147], off
	v_lshl_add_u64 v[146:147], s[34:35], 0, v[140:141]
	s_add_i32 m0, s45, 0xe000
	s_nop 0
	global_load_lds_dwordx4 v[146:147], off
	s_waitcnt vmcnt(8)
	s_waitcnt lgkmcnt(0)
	s_barrier
	s_setprio 1
	s_waitcnt lgkmcnt(0)
	v_mfma_f32_16x16x32_bf16 v[124:127], v[142:145], v[182:185], 0
	v_mfma_f32_16x16x32_bf16 v[120:123], v[158:161], v[182:185], 0
	v_mfma_f32_16x16x32_bf16 v[116:119], v[142:145], v[190:193], 0
	v_mfma_f32_16x16x32_bf16 v[112:115], v[158:161], v[190:193], 0
	v_mfma_f32_16x16x32_bf16 v[96:99], v[142:145], v[198:201], 0
	v_mfma_f32_16x16x32_bf16 v[88:91], v[158:161], v[198:201], 0
	v_mfma_f32_16x16x32_bf16 v[80:83], v[142:145], v[206:209], 0
	v_mfma_f32_16x16x32_bf16 v[72:75], v[158:161], v[206:209], 0
	v_mfma_f32_16x16x32_bf16 v[124:127], v[154:157], v[186:189], v[124:127]
	v_mfma_f32_16x16x32_bf16 v[120:123], v[162:165], v[186:189], v[120:123]
	v_mfma_f32_16x16x32_bf16 v[116:119], v[154:157], v[194:197], v[116:119]
	v_mfma_f32_16x16x32_bf16 v[112:115], v[162:165], v[194:197], v[112:115]
	v_mfma_f32_16x16x32_bf16 v[96:99], v[154:157], v[202:205], v[96:99]
	v_mfma_f32_16x16x32_bf16 v[88:91], v[162:165], v[202:205], v[88:91]
	v_mfma_f32_16x16x32_bf16 v[80:83], v[154:157], v[210:213], v[80:83]
	v_mfma_f32_16x16x32_bf16 v[72:75], v[162:165], v[210:213], v[72:75]
	s_setprio 0
	s_setprio 1
	v_mfma_f32_16x16x32_bf16 v[108:111], v[166:169], v[182:185], 0
	v_mfma_f32_16x16x32_bf16 v[104:107], v[174:177], v[182:185], 0
	v_mfma_f32_16x16x32_bf16 v[100:103], v[166:169], v[190:193], 0
	v_mfma_f32_16x16x32_bf16 v[92:95], v[174:177], v[190:193], 0
	v_mfma_f32_16x16x32_bf16 v[84:87], v[166:169], v[198:201], 0
	v_mfma_f32_16x16x32_bf16 v[76:79], v[174:177], v[198:201], 0
	v_mfma_f32_16x16x32_bf16 v[68:71], v[166:169], v[206:209], 0
	v_mfma_f32_16x16x32_bf16 v[64:67], v[174:177], v[206:209], 0
	v_mfma_f32_16x16x32_bf16 v[108:111], v[170:173], v[186:189], v[108:111]
	v_mfma_f32_16x16x32_bf16 v[104:107], v[178:181], v[186:189], v[104:107]
	v_mfma_f32_16x16x32_bf16 v[100:103], v[170:173], v[194:197], v[100:103]
	v_mfma_f32_16x16x32_bf16 v[92:95], v[178:181], v[194:197], v[92:95]
	v_mfma_f32_16x16x32_bf16 v[84:87], v[170:173], v[202:205], v[84:87]
	v_mfma_f32_16x16x32_bf16 v[76:79], v[178:181], v[202:205], v[76:79]
	v_mfma_f32_16x16x32_bf16 v[68:71], v[170:173], v[210:213], v[68:71]
	v_mfma_f32_16x16x32_bf16 v[64:67], v[178:181], v[210:213], v[64:67]
	s_setprio 0
	s_barrier
	s_add_i32 s65, s56, s44
	v_lshl_add_u64 v[146:147], s[38:39], 0, v[132:133]
	s_mov_b32 m0, s65
	ds_read_b128 v[182:185], v153 offset:16384
	ds_read_b128 v[186:189], v153 offset:17408
	ds_read_b128 v[190:193], v153 offset:18432
	ds_read_b128 v[194:197], v153 offset:19456
	ds_read_b128 v[198:201], v153 offset:20480
	ds_read_b128 v[202:205], v153 offset:21504
	ds_read_b128 v[206:209], v153 offset:22528
	ds_read_b128 v[210:213], v153 offset:23552
	global_load_lds_dwordx4 v[146:147], off
	s_add_i32 m0, s65, 0x2000
	s_add_u32 s70, s38, 0x100000
	v_lshl_add_u64 v[214:215], s[38:39], 0, v[128:129]
	s_addc_u32 s71, s39, 0
	s_add_i32 s65, s57, s44
	global_load_lds_dwordx4 v[214:215], off
	v_lshl_add_u64 v[216:217], s[70:71], 0, v[132:133]
	s_mov_b32 m0, s65
	s_nop 0
	global_load_lds_dwordx4 v[216:217], off
	v_lshl_add_u64 v[216:217], s[70:71], 0, v[128:129]
	s_add_i32 m0, s65, 0x2000
	s_nop 0
	global_load_lds_dwordx4 v[216:217], off
	v_lshl_add_u64 v[216:217], s[40:41], 0, v[134:135]
	s_mov_b32 m0, s45
	s_nop 0
	global_load_lds_dwordx4 v[216:217], off
	v_lshl_add_u64 v[216:217], s[40:41], 0, v[130:131]
	s_mov_b32 m0, s47
	s_nop 0
	global_load_lds_dwordx4 v[216:217], off
	s_waitcnt vmcnt(8)
	s_waitcnt lgkmcnt(0)
	s_barrier
; #define PG8_STAGE(bufoff, gbase, voff) do { _Pragma("unroll") for (int _i = 0; _i < 2; ++_i) \
;         __builtin_amdgcn_global_load_lds((const unsigned*)((const char*)(gbase) + (voff)[_i]), (PG8_LAS unsigned*)(lds + (bufoff) + ldsw + _i * 8192), 16, 0, 0); } while (0)
; #define PG8_LDA(dst, b, h) do { _Pragma("unroll") for (int m = 0; m < 4; ++m) _Pragma("unroll") for (int k = 0; k < 2; ++k) dst[m][k] = *(const PG8_LAS bf16x8*)(lds + PG8_SA(b, h) + aoff + m * 2048 + k * 1024); } while (0)
; #define PG8_LDB(dst, b, h) do { _Pragma("unroll") for (int n = 0; n < 2; ++n) _Pragma("unroll") for (int k = 0; k < 2; ++k) dst[n][k] = *(const PG8_LAS bf16x8*)(lds + PG8_SB(b, h) + boff + n * 2048 + k * 1024); } while (0)
; #define PG8_MMA(ai, bj, At, Bt) do { __builtin_amdgcn_s_setprio(1); _Pragma("unroll") for (int m = 0; m < 4; ++m) _Pragma("unroll") for (int n = 0; n < 2; ++n) _Pragma("unroll") for (int k = 0; k < 2; ++k) \
;         acc[ai][bj][m][n] = __builtin_amdgcn_mfma_f32_16x16x32_bf16(Bt[n][k], At[m][k], acc[ai][bj][m][n], 0, 0, 0); __builtin_amdgcn_s_setprio(0); } while (0)
; #define PG8_WAIT_V(n) asm volatile("s_waitcnt vmcnt(" #n ")" ::: "memory")
; #define PG8_WAIT_L(n) asm volatile("s_waitcnt lgkmcnt(" #n ")" ::: "memory")
; #define PG8_BAR __builtin_amdgcn_s_barrier()
; #define PG8_SCHED __builtin_amdgcn_sched_barrier(0)
; template <class Epi, class Sched, bool ALIGN_EPI = false, bool SP2 = false, bool ABLK = false>
; __device__ __forceinline__ void gemm_phase(PG8_LAS unsigned char* lds, const Gemm g, const Sched& S, const Epi& E) {
;     ...
;             PG8_WAIT_V(8); PG8_WAIT_L(0); PG8_BAR; PG8_MMA(1, 0, At, B0); PG8_MMA(1, 1, At, B1); PG8_BAR; PG8_SCHED;
;             PG8_LDB(B0, 1, 0); PG8_LDB(B1, 1, 1); PG8_SCHED; PG8_LDA(At, 1, 0); PG8_STAGE(PG8_SA(0, 1), a2 + hstepA, voffA);
;             PG8_WAIT_V(8); PG8_WAIT_L(0); PG8_BAR; PG8_MMA(0, 0, At, B0); PG8_MMA(0, 1, At, B1); PG8_BAR; PG8_SCHED;
	s_setprio 1
	s_waitcnt lgkmcnt(0)
	v_mfma_f32_16x16x32_bf16 v[60:63], v[142:145], v[182:185], 0
	v_mfma_f32_16x16x32_bf16 v[56:59], v[158:161], v[182:185], 0
	v_mfma_f32_16x16x32_bf16 v[48:51], v[142:145], v[190:193], 0
	v_mfma_f32_16x16x32_bf16 v[40:43], v[158:161], v[190:193], 0
	v_mfma_f32_16x16x32_bf16 v[32:35], v[142:145], v[198:201], 0
	v_mfma_f32_16x16x32_bf16 v[24:27], v[158:161], v[198:201], 0
	v_mfma_f32_16x16x32_bf16 v[16:19], v[142:145], v[206:209], 0
	v_mfma_f32_16x16x32_bf16 v[8:11], v[158:161], v[206:209], 0
	v_mfma_f32_16x16x32_bf16 v[60:63], v[154:157], v[186:189], v[60:63]
	v_mfma_f32_16x16x32_bf16 v[56:59], v[162:165], v[186:189], v[56:59]
	v_mfma_f32_16x16x32_bf16 v[48:51], v[154:157], v[194:197], v[48:51]
	v_mfma_f32_16x16x32_bf16 v[40:43], v[162:165], v[194:197], v[40:43]
	v_mfma_f32_16x16x32_bf16 v[32:35], v[154:157], v[202:205], v[32:35]
	v_mfma_f32_16x16x32_bf16 v[24:27], v[162:165], v[202:205], v[24:27]
	v_mfma_f32_16x16x32_bf16 v[16:19], v[154:157], v[210:213], v[16:19]
	v_mfma_f32_16x16x32_bf16 v[8:11], v[162:165], v[210:213], v[8:11]
	s_setprio 0
	s_setprio 1
	v_mfma_f32_16x16x32_bf16 v[52:55], v[166:169], v[182:185], 0
	v_mfma_f32_16x16x32_bf16 v[44:47], v[174:177], v[182:185], 0
	v_mfma_f32_16x16x32_bf16 v[36:39], v[166:169], v[190:193], 0
	v_mfma_f32_16x16x32_bf16 v[28:31], v[174:177], v[190:193], 0
	v_mfma_f32_16x16x32_bf16 v[20:23], v[166:169], v[198:201], 0
	v_mfma_f32_16x16x32_bf16 v[12:15], v[174:177], v[198:201], 0
	v_mfma_f32_16x16x32_bf16 v[4:7], v[166:169], v[206:209], 0
	v_mfma_f32_16x16x32_bf16 v[0:3], v[174:177], v[206:209], 0
	v_mfma_f32_16x16x32_bf16 v[52:55], v[170:173], v[186:189], v[52:55]
	v_mfma_f32_16x16x32_bf16 v[44:47], v[178:181], v[186:189], v[44:47]
	v_mfma_f32_16x16x32_bf16 v[36:39], v[170:173], v[194:197], v[36:39]
	v_mfma_f32_16x16x32_bf16 v[28:31], v[178:181], v[194:197], v[28:31]
	v_mfma_f32_16x16x32_bf16 v[20:23], v[170:173], v[202:205], v[20:23]
	v_mfma_f32_16x16x32_bf16 v[12:15], v[178:181], v[202:205], v[12:15]
	v_mfma_f32_16x16x32_bf16 v[4:7], v[170:173], v[210:213], v[4:7]
	v_mfma_f32_16x16x32_bf16 v[0:3], v[178:181], v[210:213], v[0:3]
	s_setprio 0
	s_barrier
	s_add_i32 s65, 0, 0x18000
	v_add_u32_e32 v136, s65, v150
	s_add_i32 s68, 0, 0x1c000
	ds_read_b128 v[142:145], v136
	ds_read_b128 v[154:157], v136 offset:1024
	ds_read_b128 v[158:161], v136 offset:2048
	ds_read_b128 v[162:165], v136 offset:3072
	v_add_u32_e32 v136, s68, v150
	ds_read_b128 v[166:169], v136
	ds_read_b128 v[170:173], v136 offset:1024
	ds_read_b128 v[174:177], v136 offset:2048
	ds_read_b128 v[178:181], v136 offset:3072
	s_add_u32 s40, s40, 0x4000
	s_addc_u32 s41, s41, 0
	s_mov_b32 m0, s48
	v_lshl_add_u64 v[216:217], s[40:41], 0, v[134:135]
	ds_read_b128 v[182:185], v153 offset:32768
	ds_read_b128 v[186:189], v153 offset:33792
	ds_read_b128 v[190:193], v153 offset:34816
	ds_read_b128 v[194:197], v153 offset:35840
	ds_read_b128 v[198:201], v153 offset:36864
	ds_read_b128 v[202:205], v153 offset:37888
	ds_read_b128 v[206:209], v153 offset:38912
	ds_read_b128 v[210:213], v153 offset:39936
	global_load_lds_dwordx4 v[216:217], off
	v_lshl_add_u64 v[216:217], s[40:41], 0, v[130:131]
	s_mov_b32 m0, s49
	s_nop 0
	global_load_lds_dwordx4 v[216:217], off
	s_waitcnt vmcnt(8)
	s_waitcnt lgkmcnt(0)
	s_barrier
	s_setprio 1
	s_waitcnt lgkmcnt(0)
	v_mfma_f32_16x16x32_bf16 v[124:127], v[142:145], v[182:185], v[124:127]
	v_mfma_f32_16x16x32_bf16 v[120:123], v[158:161], v[182:185], v[120:123]
	v_mfma_f32_16x16x32_bf16 v[116:119], v[142:145], v[190:193], v[116:119]
	v_mfma_f32_16x16x32_bf16 v[112:115], v[158:161], v[190:193], v[112:115]
	v_mfma_f32_16x16x32_bf16 v[96:99], v[142:145], v[198:201], v[96:99]
	v_mfma_f32_16x16x32_bf16 v[88:91], v[158:161], v[198:201], v[88:91]
	v_mfma_f32_16x16x32_bf16 v[80:83], v[142:145], v[206:209], v[80:83]
	v_mfma_f32_16x16x32_bf16 v[72:75], v[158:161], v[206:209], v[72:75]
	v_mfma_f32_16x16x32_bf16 v[124:127], v[154:157], v[186:189], v[124:127]
	v_mfma_f32_16x16x32_bf16 v[120:123], v[162:165], v[186:189], v[120:123]
	v_mfma_f32_16x16x32_bf16 v[116:119], v[154:157], v[194:197], v[116:119]
	v_mfma_f32_16x16x32_bf16 v[112:115], v[162:165], v[194:197], v[112:115]
	v_mfma_f32_16x16x32_bf16 v[96:99], v[154:157], v[202:205], v[96:99]
	v_mfma_f32_16x16x32_bf16 v[88:91], v[162:165], v[202:205], v[88:91]
	v_mfma_f32_16x16x32_bf16 v[80:83], v[154:157], v[210:213], v[80:83]
	v_mfma_f32_16x16x32_bf16 v[72:75], v[162:165], v[210:213], v[72:75]
	s_setprio 0
	s_setprio 1
	v_mfma_f32_16x16x32_bf16 v[108:111], v[166:169], v[182:185], v[108:111]
	v_mfma_f32_16x16x32_bf16 v[104:107], v[174:177], v[182:185], v[104:107]
	v_mfma_f32_16x16x32_bf16 v[100:103], v[166:169], v[190:193], v[100:103]
	v_mfma_f32_16x16x32_bf16 v[92:95], v[174:177], v[190:193], v[92:95]
	v_mfma_f32_16x16x32_bf16 v[84:87], v[166:169], v[198:201], v[84:87]
	v_mfma_f32_16x16x32_bf16 v[76:79], v[174:177], v[198:201], v[76:79]
	v_mfma_f32_16x16x32_bf16 v[68:71], v[166:169], v[206:209], v[68:71]
	v_mfma_f32_16x16x32_bf16 v[64:67], v[174:177], v[206:209], v[64:67]
	v_mfma_f32_16x16x32_bf16 v[108:111], v[170:173], v[186:189], v[108:111]
	v_mfma_f32_16x16x32_bf16 v[104:107], v[178:181], v[186:189], v[104:107]
	v_mfma_f32_16x16x32_bf16 v[100:103], v[170:173], v[194:197], v[100:103]
	v_mfma_f32_16x16x32_bf16 v[92:95], v[178:181], v[194:197], v[92:95]
	v_mfma_f32_16x16x32_bf16 v[84:87], v[170:173], v[202:205], v[84:87]
	v_mfma_f32_16x16x32_bf16 v[76:79], v[178:181], v[202:205], v[76:79]
	v_mfma_f32_16x16x32_bf16 v[68:71], v[170:173], v[210:213], v[68:71]
	v_mfma_f32_16x16x32_bf16 v[64:67], v[178:181], v[210:213], v[64:67]
	s_setprio 0
	s_barrier
; #define PG8_STAGE(bufoff, gbase, voff) do { _Pragma("unroll") for (int _i = 0; _i < 2; ++_i) \
;         __builtin_amdgcn_global_load_lds((const unsigned*)((const char*)(gbase) + (voff)[_i]), (PG8_LAS unsigned*)(lds + (bufoff) + ldsw + _i * 8192), 16, 0, 0); } while (0)
; #define PG8_LDA(dst, b, h) do { _Pragma("unroll") for (int m = 0; m < 4; ++m) _Pragma("unroll") for (int k = 0; k < 2; ++k) dst[m][k] = *(const PG8_LAS bf16x8*)(lds + PG8_SA(b, h) + aoff + m * 2048 + k * 1024); } while (0)
; #define PG8_MMA(ai, bj, At, Bt) do { __builtin_amdgcn_s_setprio(1); _Pragma("unroll") for (int m = 0; m < 4; ++m) _Pragma("unroll") for (int n = 0; n < 2; ++n) _Pragma("unroll") for (int k = 0; k < 2; ++k) \
;         acc[ai][bj][m][n] = __builtin_amdgcn_mfma_f32_16x16x32_bf16(Bt[n][k], At[m][k], acc[ai][bj][m][n], 0, 0, 0); __builtin_amdgcn_s_setprio(0); } while (0)
; #define PG8_WAIT_V(n) asm volatile("s_waitcnt vmcnt(" #n ")" ::: "memory")
; #define PG8_WAIT_L(n) asm volatile("s_waitcnt lgkmcnt(" #n ")" ::: "memory")
; #define PG8_BAR __builtin_amdgcn_s_barrier()
; #define PG8_SCHED __builtin_amdgcn_sched_barrier(0)
; template <class Epi, class Sched, bool ALIGN_EPI = false, bool SP2 = false, bool ABLK = false>
; __device__ __forceinline__ void gemm_phase(PG8_LAS unsigned char* lds, const Gemm g, const Sched& S, const Epi& E) {
;     ...
;         for (int t = 0; t < nt; t += 2) {
;     ...
;             PG8_LDA(At, 1, 1); PG8_STAGE(PG8_SB(1, 0), b3, voffB); PG8_STAGE(PG8_SB(1, 1), b3 + hstep, voffB); PG8_STAGE(PG8_SA(1, 0), a3, voffA);
;             PG8_WAIT_V(8); PG8_WAIT_L(0); PG8_BAR; PG8_MMA(1, 0, At, B0); PG8_MMA(1, 1, At, B1); PG8_BAR; PG8_SCHED;
	s_add_i32 s40, s65, s44
	v_lshl_add_u64 v[146:147], v[146:147], 0, s[4:5]
	s_mov_b32 m0, s40
	ds_read_b128 v[182:185], v153 offset:49152
	ds_read_b128 v[186:189], v153 offset:50176
	ds_read_b128 v[190:193], v153 offset:51200
	ds_read_b128 v[194:197], v153 offset:52224
	ds_read_b128 v[198:201], v153 offset:53248
	ds_read_b128 v[202:205], v153 offset:54272
	ds_read_b128 v[206:209], v153 offset:55296
	ds_read_b128 v[210:213], v153 offset:56320
	global_load_lds_dwordx4 v[146:147], off
	s_add_i32 m0, s40, 0x2000
	s_add_u32 s38, s38, 0x100080
	v_lshl_add_u64 v[146:147], v[214:215], 0, s[4:5]
	s_addc_u32 s39, s39, 0
	s_add_i32 s40, s68, s44
	global_load_lds_dwordx4 v[146:147], off
	v_lshl_add_u64 v[146:147], s[38:39], 0, v[132:133]
	s_mov_b32 m0, s40
	s_nop 0
	global_load_lds_dwordx4 v[146:147], off
	v_lshl_add_u64 v[146:147], s[38:39], 0, v[128:129]
	s_add_i32 m0, s40, 0x2000
	s_nop 0
	global_load_lds_dwordx4 v[146:147], off
	v_lshl_add_u64 v[146:147], s[36:37], 0, v[134:135]
	s_mov_b32 m0, s54
	s_nop 0
	global_load_lds_dwordx4 v[146:147], off
	v_lshl_add_u64 v[146:147], s[36:37], 0, v[130:131]
	s_mov_b32 m0, s55
	s_nop 0
	global_load_lds_dwordx4 v[146:147], off
	s_waitcnt vmcnt(8)
	s_waitcnt lgkmcnt(0)
	s_barrier
	s_setprio 1
	s_waitcnt lgkmcnt(0)
	v_mfma_f32_16x16x32_bf16 v[60:63], v[142:145], v[182:185], v[60:63]
	v_mfma_f32_16x16x32_bf16 v[56:59], v[158:161], v[182:185], v[56:59]
	v_mfma_f32_16x16x32_bf16 v[48:51], v[142:145], v[190:193], v[48:51]
	v_mfma_f32_16x16x32_bf16 v[40:43], v[158:161], v[190:193], v[40:43]
	v_mfma_f32_16x16x32_bf16 v[32:35], v[142:145], v[198:201], v[32:35]
	v_mfma_f32_16x16x32_bf16 v[24:27], v[158:161], v[198:201], v[24:27]
	v_mfma_f32_16x16x32_bf16 v[16:19], v[142:145], v[206:209], v[16:19]
	v_mfma_f32_16x16x32_bf16 v[8:11], v[158:161], v[206:209], v[8:11]
	v_mfma_f32_16x16x32_bf16 v[60:63], v[154:157], v[186:189], v[60:63]
	v_mfma_f32_16x16x32_bf16 v[56:59], v[162:165], v[186:189], v[56:59]
	v_mfma_f32_16x16x32_bf16 v[48:51], v[154:157], v[194:197], v[48:51]
	v_mfma_f32_16x16x32_bf16 v[40:43], v[162:165], v[194:197], v[40:43]
	v_mfma_f32_16x16x32_bf16 v[32:35], v[154:157], v[202:205], v[32:35]
	v_mfma_f32_16x16x32_bf16 v[24:27], v[162:165], v[202:205], v[24:27]
	v_mfma_f32_16x16x32_bf16 v[16:19], v[154:157], v[210:213], v[16:19]
	v_mfma_f32_16x16x32_bf16 v[8:11], v[162:165], v[210:213], v[8:11]
	s_setprio 0
	s_setprio 1
	v_mfma_f32_16x16x32_bf16 v[52:55], v[166:169], v[182:185], v[52:55]
	v_mfma_f32_16x16x32_bf16 v[44:47], v[174:177], v[182:185], v[44:47]
	v_mfma_f32_16x16x32_bf16 v[36:39], v[166:169], v[190:193], v[36:39]
	v_mfma_f32_16x16x32_bf16 v[28:31], v[174:177], v[190:193], v[28:31]
	v_mfma_f32_16x16x32_bf16 v[20:23], v[166:169], v[198:201], v[20:23]
	v_mfma_f32_16x16x32_bf16 v[12:15], v[174:177], v[198:201], v[12:15]
	v_mfma_f32_16x16x32_bf16 v[4:7], v[166:169], v[206:209], v[4:7]
	v_mfma_f32_16x16x32_bf16 v[0:3], v[174:177], v[206:209], v[0:3]
	v_mfma_f32_16x16x32_bf16 v[52:55], v[170:173], v[186:189], v[52:55]
	v_mfma_f32_16x16x32_bf16 v[44:47], v[178:181], v[186:189], v[44:47]
	v_mfma_f32_16x16x32_bf16 v[36:39], v[170:173], v[194:197], v[36:39]
	v_mfma_f32_16x16x32_bf16 v[28:31], v[178:181], v[194:197], v[28:31]
	v_mfma_f32_16x16x32_bf16 v[20:23], v[170:173], v[202:205], v[20:23]
	v_mfma_f32_16x16x32_bf16 v[12:15], v[178:181], v[202:205], v[12:15]
	v_mfma_f32_16x16x32_bf16 v[4:7], v[170:173], v[210:213], v[4:7]
	v_mfma_f32_16x16x32_bf16 v[0:3], v[178:181], v[210:213], v[0:3]
	s_setprio 0
	s_barrier
	s_add_i32 s64, s64, 2
	s_add_u32 s62, s62, 0x100
	s_addc_u32 s63, s63, 0
	s_add_u32 s34, s34, 0x10000
	s_addc_u32 s35, s35, 0
	s_cmp_gt_u32 s64, 61
	s_cbranch_scc0 .LBB0_578
	s_branch .Lp5_kdone

; #define PG8_BAR __builtin_amdgcn_s_barrier()
; template <class Epi, class Sched, bool ALIGN_EPI = false, bool SP2 = false, bool ABLK = false>
; __device__ __forceinline__ void gemm_phase(PG8_LAS unsigned char* lds, const Gemm g, const Sched& S, const Epi& E) {
;     ...
;         if constexpr (ALIGN_EPI) { if (wr == 0) PG8_BAR; }
.Lp5_kdone:
	s_and_b64 vcc, exec, s[6:7]
	s_cbranch_vccz .LBB0_581
	s_barrier
